# weight transposes 3-way: phase 0 it<128, phase-2 tail (blocks 32+) 4 its incl gate weights, phase-4 tail (blocks 64+) rest
# speedup vs baseline: 1.0001x; 1.0001x over previous
.LBB0_971:
	s_barrier
	v_readlane_b32 s32, v249, 18
	s_cmpk_eq_i32 s32, 0x100
	s_cbranch_scc0 .Ltr4_done
	s_cmpk_lt_i32 s92, 0x40
	s_cbranch_scc1 .Ltr4_done
	v_mov_b32_e32 v46, v163
	s_waitcnt vmcnt(0) lgkmcnt(0)
	v_ashrrev_i32_e32 v1, 7, v46
	s_movk_i32 s0, 0x4100
	v_mul_lo_u32 v0, v1, s0
	v_add_u32_e32 v3, 0, v0
	v_and_b32_e32 v2, 15, v46
	v_lshlrev_b32_e32 v0, 2, v2
	v_lshl_add_u32 v4, v2, 4, v3
	v_bfe_u32 v11, v46, 1, 6
	v_and_b32_e32 v2, 0x60, v46
	v_and_or_b32 v12, v11, 15, v2
	v_lshlrev_b32_e32 v2, 5, v46
	v_bfe_u32 v10, v46, 4, 3
	v_and_b32_e32 v2, 32, v2
	v_lshl_add_u32 v3, v11, 2, v3
	v_mul_u32_u24_e32 v5, 0x104, v2
	v_mul_u32_u24_e32 v6, 0x104, v10
	v_readlane_b32 s0, v254, 20
	v_lshlrev_b32_e32 v160, 2, v0
	v_add_u32_e32 v14, v4, v6
	v_add_u32_e32 v13, s0, v1
	v_add_u32_e32 v13, 0xe00, v13
	v_lshlrev_b32_e32 v0, 1, v2
	v_add_u32_e32 v15, v3, v5
	s_add_i32 s10, s92, 0x380
	s_branch .Ltr4_1076
.Ltr4_1075:
	s_or_b64 exec, exec, s[0:1]
	v_readlane_b32 s0, v249, 12
	v_readlane_b32 s1, v249, 13
	v_ashrrev_i32_e32 v1, 31, v6
	v_readlane_b32 s2, v249, 14
	v_readlane_b32 s3, v249, 15
	v_mul_lo_u32 v7, v5, v6
	v_mul_lo_u32 v1, v4, v1
	v_mad_u64_u32 v[4:5], s[0:1], v4, v6, 0
	v_lshl_add_u64 v[2:3], s[2:3], 0, v[2:3]
	v_add3_u32 v5, v5, v1, v7
	v_lshl_add_u64 v[2:3], v[4:5], 1, v[2:3]
	v_add_u32_e32 v16, 0x400, v15
	v_lshl_add_u64 v[2:3], v[8:9], 1, v[2:3]
	ds_read2_b32 v[4:5], v15 offset1:65
	ds_read2_b32 v[6:7], v15 offset0:130 offset1:195
	ds_read2_b32 v[8:9], v16 offset0:4 offset1:69
	ds_read2_b32 v[16:17], v16 offset0:134 offset1:199
	v_mov_b32_e32 v1, v161
	v_lshl_add_u64 v[18:19], v[2:3], 0, v[0:1]
	v_add_u32_e32 v1, 0x800, v15
	s_waitcnt lgkmcnt(3)
	v_cvt_pk_bf16_f32 v2, v4, v5
	s_waitcnt lgkmcnt(2)
	v_cvt_pk_bf16_f32 v3, v6, v7
	s_waitcnt lgkmcnt(1)
	v_cvt_pk_bf16_f32 v4, v8, v9
	s_waitcnt lgkmcnt(0)
	v_cvt_pk_bf16_f32 v5, v16, v17
	ds_read2_b32 v[6:7], v1 offset0:8 offset1:73
	ds_read2_b32 v[8:9], v1 offset0:138 offset1:203
	v_add_u32_e32 v1, 0xc00, v15
	ds_read2_b32 v[16:17], v1 offset0:12 offset1:77
	ds_read2_b32 v[20:21], v1 offset0:142 offset1:207
	v_add_u32_e32 v1, 0x1000, v15
	global_store_dwordx4 v[18:19], v[2:5], off
	s_movk_i32 s6, 0xc0
	s_add_i32 s10, s10, s6
	s_waitcnt lgkmcnt(3)
	v_cvt_pk_bf16_f32 v2, v6, v7
	s_waitcnt lgkmcnt(2)
	v_cvt_pk_bf16_f32 v3, v8, v9
	s_waitcnt lgkmcnt(1)
	v_cvt_pk_bf16_f32 v4, v16, v17
	s_waitcnt lgkmcnt(0)
	v_cvt_pk_bf16_f32 v5, v20, v21
	ds_read2_b32 v[6:7], v1 offset0:16 offset1:81
	ds_read2_b32 v[8:9], v1 offset0:146 offset1:211
	v_add_u32_e32 v1, 0x1400, v15
	ds_read2_b32 v[16:17], v1 offset0:20 offset1:85
	ds_read2_b32 v[20:21], v1 offset0:150 offset1:215
	v_add_u32_e32 v1, 0x1800, v15
	global_store_dwordx4 v[18:19], v[2:5], off offset:16
	s_movk_i32 s0, 0x300
	s_cmpk_gt_i32 s10, 0x5bf
	s_waitcnt lgkmcnt(3)
	v_cvt_pk_bf16_f32 v2, v6, v7
	s_waitcnt lgkmcnt(2)
	v_cvt_pk_bf16_f32 v3, v8, v9
	s_waitcnt lgkmcnt(1)
	v_cvt_pk_bf16_f32 v4, v16, v17
	s_waitcnt lgkmcnt(0)
	v_cvt_pk_bf16_f32 v5, v20, v21
	ds_read2_b32 v[6:7], v1 offset0:24 offset1:89
	ds_read2_b32 v[8:9], v1 offset0:154 offset1:219
	v_add_u32_e32 v1, 0x1c00, v15
	ds_read2_b32 v[16:17], v1 offset0:28 offset1:93
	ds_read2_b32 v[20:21], v1 offset0:158 offset1:223
	v_add_u32_e32 v13, s0, v13
	v_readlane_b32 s4, v249, 16
	v_readlane_b32 s5, v249, 17
	v_readlane_b32 s7, v249, 19
	global_store_dwordx4 v[18:19], v[2:5], off offset:32
	s_waitcnt lgkmcnt(3)
	s_nop 0
	v_cvt_pk_bf16_f32 v2, v6, v7
	s_waitcnt lgkmcnt(2)
	v_cvt_pk_bf16_f32 v3, v8, v9
	s_waitcnt lgkmcnt(1)
	v_cvt_pk_bf16_f32 v4, v16, v17
	s_waitcnt lgkmcnt(0)
	v_cvt_pk_bf16_f32 v5, v20, v21
	global_store_dwordx4 v[18:19], v[2:5], off offset:48
	s_barrier
	s_cbranch_scc1 .Ltr4_done

.Ltr4_done:
.LBB0_972:
	s_mov_b64 s[0:1], 0

.Ltr2_1075:
	s_or_b64 exec, exec, s[0:1]
	v_readlane_b32 s0, v249, 12
	v_readlane_b32 s1, v249, 13
	v_ashrrev_i32_e32 v1, 31, v6
	v_readlane_b32 s2, v249, 14
	v_readlane_b32 s3, v249, 15
	v_mul_lo_u32 v7, v5, v6
	v_mul_lo_u32 v1, v4, v1
	v_mad_u64_u32 v[4:5], s[0:1], v4, v6, 0
	v_lshl_add_u64 v[2:3], s[2:3], 0, v[2:3]
	v_add3_u32 v5, v5, v1, v7
	v_lshl_add_u64 v[2:3], v[4:5], 1, v[2:3]
	v_add_u32_e32 v16, 0x400, v15
	v_lshl_add_u64 v[2:3], v[8:9], 1, v[2:3]
	ds_read2_b32 v[4:5], v15 offset1:65
	ds_read2_b32 v[6:7], v15 offset0:130 offset1:195
	ds_read2_b32 v[8:9], v16 offset0:4 offset1:69
	ds_read2_b32 v[16:17], v16 offset0:134 offset1:199
	v_mov_b32_e32 v1, v161
	v_lshl_add_u64 v[18:19], v[2:3], 0, v[0:1]
	v_add_u32_e32 v1, 0x800, v15
	s_waitcnt lgkmcnt(3)
	v_cvt_pk_bf16_f32 v2, v4, v5
	s_waitcnt lgkmcnt(2)
	v_cvt_pk_bf16_f32 v3, v6, v7
	s_waitcnt lgkmcnt(1)
	v_cvt_pk_bf16_f32 v4, v8, v9
	s_waitcnt lgkmcnt(0)
	v_cvt_pk_bf16_f32 v5, v16, v17
	ds_read2_b32 v[6:7], v1 offset0:8 offset1:73
	ds_read2_b32 v[8:9], v1 offset0:138 offset1:203
	v_add_u32_e32 v1, 0xc00, v15
	ds_read2_b32 v[16:17], v1 offset0:12 offset1:77
	ds_read2_b32 v[20:21], v1 offset0:142 offset1:207
	v_add_u32_e32 v1, 0x1000, v15
	global_store_dwordx4 v[18:19], v[2:5], off
	s_movk_i32 s6, 0xe0
	s_add_i32 s10, s10, s6
	s_movk_i32 s32, 0x380
	s_cmpk_gt_i32 s10, 0x3bf
	s_cselect_b32 s32, 0xb80, s32
	s_waitcnt lgkmcnt(3)
	v_cvt_pk_bf16_f32 v2, v6, v7
	s_waitcnt lgkmcnt(2)
	v_cvt_pk_bf16_f32 v3, v8, v9
	s_waitcnt lgkmcnt(1)
	v_cvt_pk_bf16_f32 v4, v16, v17
	s_waitcnt lgkmcnt(0)
	v_cvt_pk_bf16_f32 v5, v20, v21
	ds_read2_b32 v[6:7], v1 offset0:16 offset1:81
	ds_read2_b32 v[8:9], v1 offset0:146 offset1:211
	v_add_u32_e32 v1, 0x1400, v15
	ds_read2_b32 v[16:17], v1 offset0:20 offset1:85
	ds_read2_b32 v[20:21], v1 offset0:150 offset1:215
	v_add_u32_e32 v1, 0x1800, v15
	global_store_dwordx4 v[18:19], v[2:5], off offset:16
	s_mov_b32 s0, s32
	s_cmpk_gt_i32 s10, 0x3ff
	s_waitcnt lgkmcnt(3)
	v_cvt_pk_bf16_f32 v2, v6, v7
	s_waitcnt lgkmcnt(2)
	v_cvt_pk_bf16_f32 v3, v8, v9
	s_waitcnt lgkmcnt(1)
	v_cvt_pk_bf16_f32 v4, v16, v17
	s_waitcnt lgkmcnt(0)
	v_cvt_pk_bf16_f32 v5, v20, v21
	ds_read2_b32 v[6:7], v1 offset0:24 offset1:89
	ds_read2_b32 v[8:9], v1 offset0:154 offset1:219
	v_add_u32_e32 v1, 0x1c00, v15
	ds_read2_b32 v[16:17], v1 offset0:28 offset1:93
	ds_read2_b32 v[20:21], v1 offset0:158 offset1:223
	v_add_u32_e32 v13, s0, v13
	v_readlane_b32 s4, v249, 16
	v_readlane_b32 s5, v249, 17
	v_readlane_b32 s7, v249, 19
	global_store_dwordx4 v[18:19], v[2:5], off offset:32
	s_waitcnt lgkmcnt(3)
	s_nop 0
	v_cvt_pk_bf16_f32 v2, v6, v7
	s_waitcnt lgkmcnt(2)
	v_cvt_pk_bf16_f32 v3, v8, v9
	s_waitcnt lgkmcnt(1)
	v_cvt_pk_bf16_f32 v4, v16, v17
	s_waitcnt lgkmcnt(0)
	v_cvt_pk_bf16_f32 v5, v20, v21
	global_store_dwordx4 v[18:19], v[2:5], off offset:48
	s_barrier
	s_cbranch_scc1 .Ltr2_done
